# waitcnt placement: removed the loop-head s_waitcnt vmcnt(0) in the ph3 LoRA GEMM mainloop (the other six instantiations of the same 8-phase template have none; the template's own counted waits + barri
# speedup vs baseline: 1.0021x; 1.0005x over previous
.LBB0_488:
	ds_read_b128 v[64:67], v172
	ds_read_b128 v[68:71], v172 offset:1024
	ds_read_b128 v[72:75], v172 offset:2048
	ds_read_b128 v[76:79], v172 offset:3072
	ds_read_b128 v[166:169], v173
	ds_read_b128 v[176:179], v173 offset:1024
	ds_read_b128 v[182:185], v173 offset:2048
	ds_read_b128 v[186:189], v173 offset:3072
	s_add_u32 s28, s2, 0xfffe8080
	s_addc_u32 s29, s3, -1
	s_cmp_eq_u32 s53, 2
	s_cselect_b32 s39, s21, s29
	s_cselect_b32 s38, s20, s28
	s_cselect_b32 s29, s23, s52
	s_cselect_b32 s28, s22, s49
	v_lshl_add_u64 v[170:171], s[2:3], 0, v[156:157]
	s_add_i32 m0, s35, 0xc000
	ds_read_b128 v[190:193], v174
	ds_read_b128 v[194:197], v174 offset:1024
	ds_read_b128 v[198:201], v174 offset:2048
	ds_read_b128 v[202:205], v174 offset:3072
	ds_read_b128 v[206:209], v174 offset:4096
	ds_read_b128 v[212:215], v174 offset:5120
	ds_read_b128 v[216:219], v174 offset:6144
	ds_read_b128 v[220:223], v174 offset:7168
	global_load_lds_dwordx4 v[170:171], off
	v_lshl_add_u64 v[170:171], s[2:3], 0, v[158:159]
	s_add_i32 m0, s35, 0xe000
	s_nop 0
	global_load_lds_dwordx4 v[170:171], off
	s_waitcnt vmcnt(8)
	s_waitcnt lgkmcnt(0)
	s_barrier
	s_setprio 1
	s_waitcnt lgkmcnt(0)
	v_mfma_f32_16x16x32_bf16 v[140:143], v[64:67], v[190:193], v[140:143]
	v_mfma_f32_16x16x32_bf16 v[136:139], v[72:75], v[190:193], v[136:139]
	v_mfma_f32_16x16x32_bf16 v[124:127], v[64:67], v[198:201], v[124:127]
	v_mfma_f32_16x16x32_bf16 v[120:123], v[72:75], v[198:201], v[120:123]
	v_mfma_f32_16x16x32_bf16 v[108:111], v[64:67], v[206:209], v[108:111]
	v_mfma_f32_16x16x32_bf16 v[104:107], v[72:75], v[206:209], v[104:107]
	v_mfma_f32_16x16x32_bf16 v[92:95], v[64:67], v[216:219], v[92:95]
	v_mfma_f32_16x16x32_bf16 v[88:91], v[72:75], v[216:219], v[88:91]
	v_mfma_f32_16x16x32_bf16 v[140:143], v[68:71], v[194:197], v[140:143]
	v_mfma_f32_16x16x32_bf16 v[136:139], v[76:79], v[194:197], v[136:139]
	v_mfma_f32_16x16x32_bf16 v[124:127], v[68:71], v[202:205], v[124:127]
	v_mfma_f32_16x16x32_bf16 v[120:123], v[76:79], v[202:205], v[120:123]
	v_mfma_f32_16x16x32_bf16 v[108:111], v[68:71], v[212:215], v[108:111]
	v_mfma_f32_16x16x32_bf16 v[104:107], v[76:79], v[212:215], v[104:107]
	v_mfma_f32_16x16x32_bf16 v[92:95], v[68:71], v[220:223], v[92:95]
	v_mfma_f32_16x16x32_bf16 v[88:91], v[76:79], v[220:223], v[88:91]
	s_setprio 0
	s_setprio 1
	v_mfma_f32_16x16x32_bf16 v[132:135], v[166:169], v[190:193], v[132:135]
	v_mfma_f32_16x16x32_bf16 v[128:131], v[182:185], v[190:193], v[128:131]
	v_mfma_f32_16x16x32_bf16 v[116:119], v[166:169], v[198:201], v[116:119]
	v_mfma_f32_16x16x32_bf16 v[112:115], v[182:185], v[198:201], v[112:115]
	v_mfma_f32_16x16x32_bf16 v[100:103], v[166:169], v[206:209], v[100:103]
	v_mfma_f32_16x16x32_bf16 v[96:99], v[182:185], v[206:209], v[96:99]
	v_mfma_f32_16x16x32_bf16 v[84:87], v[166:169], v[216:219], v[84:87]
	v_mfma_f32_16x16x32_bf16 v[80:83], v[182:185], v[216:219], v[80:83]
	v_mfma_f32_16x16x32_bf16 v[132:135], v[176:179], v[194:197], v[132:135]
	v_mfma_f32_16x16x32_bf16 v[128:131], v[186:189], v[194:197], v[128:131]
	v_mfma_f32_16x16x32_bf16 v[116:119], v[176:179], v[202:205], v[116:119]
	v_mfma_f32_16x16x32_bf16 v[112:115], v[186:189], v[202:205], v[112:115]
	v_mfma_f32_16x16x32_bf16 v[100:103], v[176:179], v[212:215], v[100:103]
	v_mfma_f32_16x16x32_bf16 v[96:99], v[186:189], v[212:215], v[96:99]
	v_mfma_f32_16x16x32_bf16 v[84:87], v[176:179], v[220:223], v[84:87]
	v_mfma_f32_16x16x32_bf16 v[80:83], v[186:189], v[220:223], v[80:83]
	s_setprio 0
	s_barrier
	s_add_i32 s76, s63, s11
	v_lshl_add_u64 v[170:171], s[28:29], 0, v[146:147]
	s_mov_b32 m0, s76
	ds_read_b128 v[190:193], v174 offset:16384
	ds_read_b128 v[194:197], v174 offset:17408
	ds_read_b128 v[198:201], v174 offset:18432
	ds_read_b128 v[202:205], v174 offset:19456
	ds_read_b128 v[206:209], v174 offset:20480
	ds_read_b128 v[212:215], v174 offset:21504
	ds_read_b128 v[216:219], v174 offset:22528
	ds_read_b128 v[220:223], v174 offset:23552
	global_load_lds_dwordx4 v[170:171], off
	s_add_i32 m0, s76, 0x2000
	s_add_u32 s76, s28, 0x18000
	v_lshl_add_u64 v[224:225], s[28:29], 0, v[150:151]
	s_addc_u32 s77, s29, 0
	s_add_i32 s78, s64, s11
	global_load_lds_dwordx4 v[224:225], off
	v_lshl_add_u64 v[226:227], s[76:77], 0, v[146:147]
	s_mov_b32 m0, s78
	v_lshl_add_u64 v[228:229], s[38:39], 0, v[148:149]
	global_load_lds_dwordx4 v[226:227], off
	v_lshl_add_u64 v[226:227], s[76:77], 0, v[150:151]
	s_add_i32 m0, s78, 0x2000
	s_nop 0
	global_load_lds_dwordx4 v[226:227], off
	v_lshl_add_u64 v[226:227], s[38:39], 0, v[144:145]
	s_mov_b32 m0, s35
	s_nop 0
	global_load_lds_dwordx4 v[226:227], off
	s_mov_b32 m0, s54
	s_nop 0
	global_load_lds_dwordx4 v[228:229], off
	s_waitcnt vmcnt(8)
	s_waitcnt lgkmcnt(0)
	s_barrier
	s_setprio 1
	s_waitcnt lgkmcnt(0)
	v_mfma_f32_16x16x32_bf16 v[60:63], v[64:67], v[190:193], v[60:63]
	v_mfma_f32_16x16x32_bf16 v[56:59], v[72:75], v[190:193], v[56:59]
	v_mfma_f32_16x16x32_bf16 v[44:47], v[64:67], v[198:201], v[44:47]
	v_mfma_f32_16x16x32_bf16 v[40:43], v[72:75], v[198:201], v[40:43]
	v_mfma_f32_16x16x32_bf16 v[28:31], v[64:67], v[206:209], v[28:31]
	v_mfma_f32_16x16x32_bf16 v[24:27], v[72:75], v[206:209], v[24:27]
	v_mfma_f32_16x16x32_bf16 v[12:15], v[64:67], v[216:219], v[12:15]
	v_mfma_f32_16x16x32_bf16 v[8:11], v[72:75], v[216:219], v[8:11]
	v_mfma_f32_16x16x32_bf16 v[60:63], v[68:71], v[194:197], v[60:63]
	v_mfma_f32_16x16x32_bf16 v[56:59], v[76:79], v[194:197], v[56:59]
	v_mfma_f32_16x16x32_bf16 v[44:47], v[68:71], v[202:205], v[44:47]
	v_mfma_f32_16x16x32_bf16 v[40:43], v[76:79], v[202:205], v[40:43]
	v_mfma_f32_16x16x32_bf16 v[28:31], v[68:71], v[212:215], v[28:31]
	v_mfma_f32_16x16x32_bf16 v[24:27], v[76:79], v[212:215], v[24:27]
	v_mfma_f32_16x16x32_bf16 v[12:15], v[68:71], v[220:223], v[12:15]
	v_mfma_f32_16x16x32_bf16 v[8:11], v[76:79], v[220:223], v[8:11]
	s_setprio 0
	s_setprio 1
	v_mfma_f32_16x16x32_bf16 v[52:55], v[166:169], v[190:193], v[52:55]
	v_mfma_f32_16x16x32_bf16 v[48:51], v[182:185], v[190:193], v[48:51]
	v_mfma_f32_16x16x32_bf16 v[36:39], v[166:169], v[198:201], v[36:39]
	v_mfma_f32_16x16x32_bf16 v[32:35], v[182:185], v[198:201], v[32:35]
	v_mfma_f32_16x16x32_bf16 v[20:23], v[166:169], v[206:209], v[20:23]
	v_mfma_f32_16x16x32_bf16 v[16:19], v[182:185], v[206:209], v[16:19]
	v_mfma_f32_16x16x32_bf16 v[4:7], v[166:169], v[216:219], v[4:7]
	v_mfma_f32_16x16x32_bf16 v[0:3], v[182:185], v[216:219], v[0:3]
	v_mfma_f32_16x16x32_bf16 v[52:55], v[176:179], v[194:197], v[52:55]
	v_mfma_f32_16x16x32_bf16 v[48:51], v[186:189], v[194:197], v[48:51]
	v_mfma_f32_16x16x32_bf16 v[36:39], v[176:179], v[202:205], v[36:39]
	v_mfma_f32_16x16x32_bf16 v[32:35], v[186:189], v[202:205], v[32:35]
	v_mfma_f32_16x16x32_bf16 v[20:23], v[176:179], v[212:215], v[20:23]
	v_mfma_f32_16x16x32_bf16 v[16:19], v[186:189], v[212:215], v[16:19]
	v_mfma_f32_16x16x32_bf16 v[4:7], v[176:179], v[220:223], v[4:7]
	v_mfma_f32_16x16x32_bf16 v[0:3], v[186:189], v[220:223], v[0:3]
	s_setprio 0
	s_barrier
	s_add_i32 s76, 0, 0x18000
	s_add_i32 s77, 0, 0x1c000
	v_add_u32_e32 v76, s76, v163
	v_add_u32_e32 v175, s77, v163
	ds_read_b128 v[64:67], v76
	ds_read_b128 v[68:71], v76 offset:1024
	ds_read_b128 v[72:75], v76 offset:2048
	ds_read_b128 v[76:79], v76 offset:3072
	ds_read_b128 v[166:169], v175
	ds_read_b128 v[176:179], v175 offset:1024
	ds_read_b128 v[182:185], v175 offset:2048
	ds_read_b128 v[186:189], v175 offset:3072
	s_add_u32 s38, s38, 0x18000
	s_addc_u32 s39, s39, 0
	s_mov_b32 m0, s55
	v_lshl_add_u64 v[230:231], s[38:39], 0, v[144:145]
	ds_read_b128 v[190:193], v174 offset:32768
	ds_read_b128 v[194:197], v174 offset:33792
	ds_read_b128 v[198:201], v174 offset:34816
	ds_read_b128 v[202:205], v174 offset:35840
	ds_read_b128 v[206:209], v174 offset:36864
	ds_read_b128 v[212:215], v174 offset:37888
	ds_read_b128 v[216:219], v174 offset:38912
	ds_read_b128 v[220:223], v174 offset:39936
	global_load_lds_dwordx4 v[230:231], off
	v_lshl_add_u64 v[230:231], s[38:39], 0, v[148:149]
	s_mov_b32 m0, s56
	s_nop 0
	global_load_lds_dwordx4 v[230:231], off
	s_waitcnt vmcnt(8)
	s_waitcnt lgkmcnt(0)
	s_barrier
	s_setprio 1
	s_waitcnt lgkmcnt(0)
	v_mfma_f32_16x16x32_bf16 v[140:143], v[64:67], v[190:193], v[140:143]
	v_mfma_f32_16x16x32_bf16 v[136:139], v[72:75], v[190:193], v[136:139]
	v_mfma_f32_16x16x32_bf16 v[124:127], v[64:67], v[198:201], v[124:127]
	v_mfma_f32_16x16x32_bf16 v[120:123], v[72:75], v[198:201], v[120:123]
	v_mfma_f32_16x16x32_bf16 v[108:111], v[64:67], v[206:209], v[108:111]
	v_mfma_f32_16x16x32_bf16 v[104:107], v[72:75], v[206:209], v[104:107]
	v_mfma_f32_16x16x32_bf16 v[92:95], v[64:67], v[216:219], v[92:95]
	v_mfma_f32_16x16x32_bf16 v[88:91], v[72:75], v[216:219], v[88:91]
	v_mfma_f32_16x16x32_bf16 v[140:143], v[68:71], v[194:197], v[140:143]
	v_mfma_f32_16x16x32_bf16 v[136:139], v[76:79], v[194:197], v[136:139]
	v_mfma_f32_16x16x32_bf16 v[124:127], v[68:71], v[202:205], v[124:127]
	v_mfma_f32_16x16x32_bf16 v[120:123], v[76:79], v[202:205], v[120:123]
	v_mfma_f32_16x16x32_bf16 v[108:111], v[68:71], v[212:215], v[108:111]
	v_mfma_f32_16x16x32_bf16 v[104:107], v[76:79], v[212:215], v[104:107]
	v_mfma_f32_16x16x32_bf16 v[92:95], v[68:71], v[220:223], v[92:95]
	v_mfma_f32_16x16x32_bf16 v[88:91], v[76:79], v[220:223], v[88:91]
	s_setprio 0
	s_setprio 1
	v_mfma_f32_16x16x32_bf16 v[132:135], v[166:169], v[190:193], v[132:135]
	v_mfma_f32_16x16x32_bf16 v[128:131], v[182:185], v[190:193], v[128:131]
	v_mfma_f32_16x16x32_bf16 v[116:119], v[166:169], v[198:201], v[116:119]
	v_mfma_f32_16x16x32_bf16 v[112:115], v[182:185], v[198:201], v[112:115]
	v_mfma_f32_16x16x32_bf16 v[100:103], v[166:169], v[206:209], v[100:103]
	v_mfma_f32_16x16x32_bf16 v[96:99], v[182:185], v[206:209], v[96:99]
	v_mfma_f32_16x16x32_bf16 v[84:87], v[166:169], v[216:219], v[84:87]
	v_mfma_f32_16x16x32_bf16 v[80:83], v[182:185], v[216:219], v[80:83]
	v_mfma_f32_16x16x32_bf16 v[132:135], v[176:179], v[194:197], v[132:135]
	v_mfma_f32_16x16x32_bf16 v[128:131], v[186:189], v[194:197], v[128:131]
	v_mfma_f32_16x16x32_bf16 v[116:119], v[176:179], v[202:205], v[116:119]
	v_mfma_f32_16x16x32_bf16 v[112:115], v[186:189], v[202:205], v[112:115]
	v_mfma_f32_16x16x32_bf16 v[100:103], v[176:179], v[212:215], v[100:103]
	v_mfma_f32_16x16x32_bf16 v[96:99], v[186:189], v[212:215], v[96:99]
	v_mfma_f32_16x16x32_bf16 v[84:87], v[176:179], v[220:223], v[84:87]
	v_mfma_f32_16x16x32_bf16 v[80:83], v[186:189], v[220:223], v[80:83]
	s_setprio 0
	s_barrier
	s_add_i32 s38, s76, s11
	v_lshl_add_u64 v[170:171], v[170:171], 0, s[16:17]
	s_mov_b32 m0, s38
	ds_read_b128 v[190:193], v174 offset:49152
	ds_read_b128 v[194:197], v174 offset:50176
	ds_read_b128 v[198:201], v174 offset:51200
	ds_read_b128 v[202:205], v174 offset:52224
	ds_read_b128 v[206:209], v174 offset:53248
	ds_read_b128 v[212:215], v174 offset:54272
	ds_read_b128 v[216:219], v174 offset:55296
	ds_read_b128 v[220:223], v174 offset:56320
	global_load_lds_dwordx4 v[170:171], off
	s_add_i32 m0, s38, 0x2000
	s_add_u32 s28, s28, 0x18080
	v_lshl_add_u64 v[170:171], v[224:225], 0, s[16:17]
	s_addc_u32 s29, s29, 0
	s_add_i32 s38, s77, s11
	global_load_lds_dwordx4 v[170:171], off
	v_lshl_add_u64 v[170:171], s[28:29], 0, v[146:147]
	s_mov_b32 m0, s38
	s_nop 0
	global_load_lds_dwordx4 v[170:171], off
	v_lshl_add_u64 v[170:171], s[28:29], 0, v[150:151]
	s_add_i32 m0, s38, 0x2000
	s_nop 0
	global_load_lds_dwordx4 v[170:171], off
	v_lshl_add_u64 v[170:171], v[226:227], 0, s[16:17]
	s_mov_b32 m0, s61
	s_nop 0
	global_load_lds_dwordx4 v[170:171], off
	v_lshl_add_u64 v[170:171], v[228:229], 0, s[16:17]
	s_mov_b32 m0, s62
	s_nop 0
	global_load_lds_dwordx4 v[170:171], off
	s_waitcnt vmcnt(8)
	s_waitcnt lgkmcnt(0)
	s_barrier
	s_setprio 1
	s_waitcnt lgkmcnt(0)
	v_mfma_f32_16x16x32_bf16 v[60:63], v[64:67], v[190:193], v[60:63]
	v_mfma_f32_16x16x32_bf16 v[56:59], v[72:75], v[190:193], v[56:59]
	v_mfma_f32_16x16x32_bf16 v[44:47], v[64:67], v[198:201], v[44:47]
	v_mfma_f32_16x16x32_bf16 v[40:43], v[72:75], v[198:201], v[40:43]
	v_mfma_f32_16x16x32_bf16 v[28:31], v[64:67], v[206:209], v[28:31]
	v_mfma_f32_16x16x32_bf16 v[24:27], v[72:75], v[206:209], v[24:27]
	v_mfma_f32_16x16x32_bf16 v[12:15], v[64:67], v[216:219], v[12:15]
	v_mfma_f32_16x16x32_bf16 v[8:11], v[72:75], v[216:219], v[8:11]
	v_mfma_f32_16x16x32_bf16 v[60:63], v[68:71], v[194:197], v[60:63]
	v_mfma_f32_16x16x32_bf16 v[56:59], v[76:79], v[194:197], v[56:59]
	v_mfma_f32_16x16x32_bf16 v[44:47], v[68:71], v[202:205], v[44:47]
	v_mfma_f32_16x16x32_bf16 v[40:43], v[76:79], v[202:205], v[40:43]
	v_mfma_f32_16x16x32_bf16 v[28:31], v[68:71], v[212:215], v[28:31]
	v_mfma_f32_16x16x32_bf16 v[24:27], v[76:79], v[212:215], v[24:27]
	v_mfma_f32_16x16x32_bf16 v[12:15], v[68:71], v[220:223], v[12:15]
	v_mfma_f32_16x16x32_bf16 v[8:11], v[76:79], v[220:223], v[8:11]
	s_setprio 0
	s_setprio 1
	v_mfma_f32_16x16x32_bf16 v[52:55], v[166:169], v[190:193], v[52:55]
	v_mfma_f32_16x16x32_bf16 v[48:51], v[182:185], v[190:193], v[48:51]
	v_mfma_f32_16x16x32_bf16 v[36:39], v[166:169], v[198:201], v[36:39]
	v_mfma_f32_16x16x32_bf16 v[32:35], v[182:185], v[198:201], v[32:35]
	v_mfma_f32_16x16x32_bf16 v[20:23], v[166:169], v[206:209], v[20:23]
	v_mfma_f32_16x16x32_bf16 v[16:19], v[182:185], v[206:209], v[16:19]
	v_mfma_f32_16x16x32_bf16 v[4:7], v[166:169], v[216:219], v[4:7]
	v_mfma_f32_16x16x32_bf16 v[0:3], v[182:185], v[216:219], v[0:3]
	v_mfma_f32_16x16x32_bf16 v[52:55], v[176:179], v[194:197], v[52:55]
	v_mfma_f32_16x16x32_bf16 v[48:51], v[186:189], v[194:197], v[48:51]
	v_mfma_f32_16x16x32_bf16 v[36:39], v[176:179], v[202:205], v[36:39]
	v_mfma_f32_16x16x32_bf16 v[32:35], v[186:189], v[202:205], v[32:35]
	v_mfma_f32_16x16x32_bf16 v[20:23], v[176:179], v[212:215], v[20:23]
	v_mfma_f32_16x16x32_bf16 v[16:19], v[186:189], v[212:215], v[16:19]
	v_mfma_f32_16x16x32_bf16 v[4:7], v[176:179], v[220:223], v[4:7]
	v_mfma_f32_16x16x32_bf16 v[0:3], v[186:189], v[220:223], v[0:3]
	s_setprio 0
	s_barrier
	s_add_i32 s53, s53, 2
	s_add_u32 s2, s2, 0x100
	s_addc_u32 s3, s3, 0
	s_add_u32 s49, s49, 0x100
	s_addc_u32 s52, s52, 0
	s_cmp_gt_u32 s53, 3
	s_cbranch_scc0 .LBB0_488
	s_and_b64 vcc, exec, s[18:19]
	s_cbranch_vccz .LBB0_491
	s_barrier
